# speedup vs baseline: 1.0134x; 1.0010x over previous
; __device__ __forceinline__ void norm_fix(f32x4 (&acc)[4][4], const float* rowss, const float* shW, int N, int brow, int bcol,
;                                          int wr, int wc, int fr, int fq) {
;   int mr = brow >> 12;
;   float sw[4];
; #pragma unroll
;   for (int n = 0; n < 4; n++) sw[n] = shW[(size_t)mr * N + bcol + (n >> 1) * 128 + wc * 32 + (n & 1) * 16 + fr];
; #pragma unroll
;   for (int m = 0; m < 4; m++)
; #pragma unroll
;     for (int j = 0; j < 4; j++) {
;       float rs = rsqrtf(rowss[brow + wr * 64 + m * 16 + fq * 4 + j] * (1.f / D) + 1e-6f);
; #pragma unroll
;       for (int n = 0; n < 4; n++) acc[m][n][j] = acc[m][n][j] * rs + sw[n];
;     }
.LBB0_1091:
	s_ashr_i32 s49, s48, 31
	s_cmpk_gt_i32 s46, 0x7fff
	s_cselect_b64 s[82:83], -1, 0
	s_cmp_lt_i32 s46, 0x8000
	s_cselect_b64 s[58:59], -1, 0
	s_and_b64 vcc, exec, s[82:83]
	v_lshlrev_b32_e32 v161, 2, v128
	s_cbranch_vccnz .LBB0_1093
	s_ashr_i32 s2, s46, 12
	s_ashr_i32 s3, s2, 31
	s_lshl_b64 s[2:3], s[2:3], 13
	s_add_u32 s39, s35, s2
	s_addc_u32 s43, s90, s3
	s_lshl_b64 s[2:3], s[48:49], 2
	s_add_u32 s2, s39, s2
	s_addc_u32 s3, s43, s3
	s_lshl_b32 s39, s76, 2
	v_add_u32_e32 v150, s46, v145
	s_add_u32 s2, s2, s39
	v_ashrrev_i32_e32 v151, 31, v150
	s_addc_u32 s3, s3, 0
	v_lshl_add_u64 v[148:149], v[150:151], 2, s[4:5]
	global_load_dword v146, v161, s[2:3]
	global_load_dword v144, v161, s[2:3] offset:64
	global_load_dword v142, v161, s[2:3] offset:512
	global_load_dword v132, v161, s[2:3] offset:576
	global_load_dwordx4 v[224:227], v[148:149], off offset:64
	global_load_dwordx4 v[228:231], v[148:149], off offset:128
	global_load_dwordx4 v[232:235], v[148:149], off offset:192
	global_load_dwordx4 v[152:155], v[148:149], off
	s_mov_b32 s2, 0x358637bd
	v_mov_b64_e32 v[148:149], s[2:3]
	s_mov_b32 s37, 12
	s_movk_i32 s51, 0xfff
	s_waitcnt vmcnt(0)
	v_pk_fma_f32 v[152:153], v[152:153], s[26:27], v[148:149] op_sel_hi:[1,0,0]
	s_nop 0
	v_mul_f32_e32 v143, 0x4b800000, v152
	v_cmp_gt_f32_e64 s[2:3], s6, v152
	v_cmp_gt_f32_e32 vcc, s6, v153
	v_pk_fma_f32 v[154:155], v[154:155], s[26:27], v[148:149] op_sel_hi:[1,0,0]
	v_cndmask_b32_e64 v143, v152, v143, s[2:3]
	v_rsq_f32_e32 v152, v143
	v_mul_f32_e32 v143, 0x4b800000, v153
	v_cndmask_b32_e32 v143, v153, v143, vcc
	v_rsq_f32_e32 v153, v143
	v_mul_f32_e32 v143, 0x4b800000, v154
	v_pk_mul_f32 v[162:163], v[152:153], s[30:31] op_sel_hi:[1,0]
	s_nop 0
	v_cndmask_b32_e64 v152, v152, v162, s[2:3]
	v_cmp_gt_f32_e64 s[2:3], s6, v154
	v_cndmask_b32_e32 v153, v153, v163, vcc
	v_cmp_gt_f32_e32 vcc, s6, v155
	v_cndmask_b32_e64 v143, v154, v143, s[2:3]
	v_rsq_f32_e32 v154, v143
	v_mul_f32_e32 v143, 0x4b800000, v155
	v_cndmask_b32_e32 v143, v155, v143, vcc
	v_rsq_f32_e32 v155, v143
	v_pk_fma_f32 v[116:117], v[116:117], v[152:153], v[146:147] op_sel_hi:[1,1,0]
	v_pk_fma_f32 v[112:113], v[112:113], v[152:153], v[144:145] op_sel_hi:[1,1,0]
	v_pk_fma_f32 v[124:125], v[124:125], v[152:153], v[142:143] op_sel_hi:[1,1,0]
	v_pk_mul_f32 v[162:163], v[154:155], s[30:31] op_sel_hi:[1,0]
	v_pk_fma_f32 v[120:121], v[120:121], v[152:153], v[132:133] op_sel_hi:[1,1,0]
	v_cndmask_b32_e32 v155, v155, v163, vcc
	v_cndmask_b32_e64 v154, v154, v162, s[2:3]
	v_pk_fma_f32 v[118:119], v[118:119], v[154:155], v[146:147] op_sel_hi:[1,1,0]
	v_pk_fma_f32 v[114:115], v[114:115], v[154:155], v[144:145] op_sel_hi:[1,1,0]
	v_pk_fma_f32 v[126:127], v[126:127], v[154:155], v[142:143] op_sel_hi:[1,1,0]
	v_pk_fma_f32 v[122:123], v[122:123], v[154:155], v[132:133] op_sel_hi:[1,1,0]
	v_add_u32_e32 v152, 16, v150
	v_add_u32_e32 v154, 17, v150
	v_ashrrev_i32_e32 v153, 31, v152
	v_ashrrev_i32_e32 v155, 31, v154
	v_lshl_add_u64 v[152:153], v[152:153], 2, s[4:5]
	v_lshl_add_u64 v[154:155], v[154:155], 2, s[4:5]
	v_mov_b32_e32 v152, v224
	v_add_u32_e32 v162, 19, v150
	v_mov_b32_e32 v153, v225
	v_ashrrev_i32_e32 v163, 31, v162
	v_lshl_add_u64 v[162:163], v[162:163], 2, s[4:5]
	s_waitcnt vmcnt(0)
	v_pk_fma_f32 v[152:153], v[152:153], s[26:27], v[148:149] op_sel_hi:[1,0,0]
	s_nop 0
	v_mul_f32_e32 v143, 0x4b800000, v152
	v_cmp_gt_f32_e64 s[2:3], s6, v152
	v_cmp_gt_f32_e32 vcc, s6, v153
	s_nop 0
	v_cndmask_b32_e64 v143, v152, v143, s[2:3]
	v_rsq_f32_e32 v152, v143
	v_mul_f32_e32 v143, 0x4b800000, v153
	v_cndmask_b32_e32 v143, v153, v143, vcc
	v_rsq_f32_e32 v153, v143
	s_nop 0
	v_pk_mul_f32 v[154:155], v[152:153], s[30:31] op_sel_hi:[1,0]
	s_nop 0
	v_cndmask_b32_e64 v152, v152, v154, s[2:3]
	v_add_u32_e32 v154, 18, v150
	v_cndmask_b32_e32 v153, v153, v155, vcc
	v_ashrrev_i32_e32 v155, 31, v154
	v_lshl_add_u64 v[154:155], v[154:155], 2, s[4:5]
	v_mov_b32_e32 v154, v226
	v_pk_fma_f32 v[100:101], v[100:101], v[152:153], v[146:147] op_sel_hi:[1,1,0]
	v_mov_b32_e32 v155, v227
	v_pk_fma_f32 v[96:97], v[96:97], v[152:153], v[144:145] op_sel_hi:[1,1,0]
	v_pk_fma_f32 v[104:105], v[104:105], v[152:153], v[132:133] op_sel_hi:[1,1,0]
	s_waitcnt vmcnt(0)
; __device__ __forceinline__ void norm_fix(f32x4 (&acc)[4][4], const float* rowss, const float* shW, int N, int brow, int bcol,
;                                          int wr, int wc, int fr, int fq) {
;   int mr = brow >> 12;
;   float sw[4];
; #pragma unroll
;   for (int n = 0; n < 4; n++) sw[n] = shW[(size_t)mr * N + bcol + (n >> 1) * 128 + wc * 32 + (n & 1) * 16 + fr];
; #pragma unroll
;   for (int m = 0; m < 4; m++)
; #pragma unroll
;     for (int j = 0; j < 4; j++) {
;       float rs = rsqrtf(rowss[brow + wr * 64 + m * 16 + fq * 4 + j] * (1.f / D) + 1e-6f);
; #pragma unroll
;       for (int n = 0; n < 4; n++) acc[m][n][j] = acc[m][n][j] * rs + sw[n];
;     }
	v_pk_fma_f32 v[154:155], v[154:155], s[26:27], v[148:149] op_sel_hi:[1,0,0]
	s_nop 0
	v_mul_f32_e32 v143, 0x4b800000, v154
	v_cmp_gt_f32_e64 s[2:3], s6, v154
	v_cmp_gt_f32_e32 vcc, s6, v155
	s_nop 0
	v_cndmask_b32_e64 v143, v154, v143, s[2:3]
	v_rsq_f32_e32 v154, v143
	v_mul_f32_e32 v143, 0x4b800000, v155
	v_cndmask_b32_e32 v143, v155, v143, vcc
	v_rsq_f32_e32 v155, v143
	v_pk_fma_f32 v[108:109], v[108:109], v[152:153], v[142:143] op_sel_hi:[1,1,0]
	v_add_u32_e32 v152, 32, v150
	v_ashrrev_i32_e32 v153, 31, v152
	v_pk_mul_f32 v[162:163], v[154:155], s[30:31] op_sel_hi:[1,0]
	v_lshl_add_u64 v[152:153], v[152:153], 2, s[4:5]
	v_cndmask_b32_e32 v155, v155, v163, vcc
	v_cndmask_b32_e64 v154, v154, v162, s[2:3]
	v_pk_fma_f32 v[102:103], v[102:103], v[154:155], v[146:147] op_sel_hi:[1,1,0]
	v_pk_fma_f32 v[98:99], v[98:99], v[154:155], v[144:145] op_sel_hi:[1,1,0]
	v_pk_fma_f32 v[110:111], v[110:111], v[154:155], v[142:143] op_sel_hi:[1,1,0]
	v_pk_fma_f32 v[106:107], v[106:107], v[154:155], v[132:133] op_sel_hi:[1,1,0]
	v_add_u32_e32 v154, 33, v150
	v_ashrrev_i32_e32 v155, 31, v154
	v_lshl_add_u64 v[154:155], v[154:155], 2, s[4:5]
	v_mov_b32_e32 v152, v228
	v_add_u32_e32 v162, 35, v150
	v_mov_b32_e32 v153, v229
	v_ashrrev_i32_e32 v163, 31, v162
	v_lshl_add_u64 v[162:163], v[162:163], 2, s[4:5]
	s_waitcnt vmcnt(0)
	v_pk_fma_f32 v[152:153], v[152:153], s[26:27], v[148:149] op_sel_hi:[1,0,0]
	s_nop 0
	v_mul_f32_e32 v143, 0x4b800000, v152
	v_cmp_gt_f32_e64 s[2:3], s6, v152
	v_cmp_gt_f32_e32 vcc, s6, v153
	s_nop 0
	v_cndmask_b32_e64 v143, v152, v143, s[2:3]
	v_rsq_f32_e32 v152, v143
	v_mul_f32_e32 v143, 0x4b800000, v153
	v_cndmask_b32_e32 v143, v153, v143, vcc
	v_rsq_f32_e32 v153, v143
	s_nop 0
	v_pk_mul_f32 v[154:155], v[152:153], s[30:31] op_sel_hi:[1,0]
	s_nop 0
	v_cndmask_b32_e64 v152, v152, v154, s[2:3]
	v_add_u32_e32 v154, 34, v150
	v_cndmask_b32_e32 v153, v153, v155, vcc
	v_ashrrev_i32_e32 v155, 31, v154
	v_lshl_add_u64 v[154:155], v[154:155], 2, s[4:5]
	v_mov_b32_e32 v154, v230
	v_pk_fma_f32 v[84:85], v[84:85], v[152:153], v[146:147] op_sel_hi:[1,1,0]
	v_mov_b32_e32 v155, v231
	v_pk_fma_f32 v[80:81], v[80:81], v[152:153], v[144:145] op_sel_hi:[1,1,0]
	v_pk_fma_f32 v[88:89], v[88:89], v[152:153], v[132:133] op_sel_hi:[1,1,0]
	s_waitcnt vmcnt(0)
	v_pk_fma_f32 v[154:155], v[154:155], s[26:27], v[148:149] op_sel_hi:[1,0,0]
	s_nop 0
	v_mul_f32_e32 v143, 0x4b800000, v154
	v_cmp_gt_f32_e64 s[2:3], s6, v154
	v_cmp_gt_f32_e32 vcc, s6, v155
	s_nop 0
	v_cndmask_b32_e64 v143, v154, v143, s[2:3]
	v_rsq_f32_e32 v154, v143
	v_mul_f32_e32 v143, 0x4b800000, v155
	v_cndmask_b32_e32 v143, v155, v143, vcc
	v_rsq_f32_e32 v155, v143
	v_pk_fma_f32 v[92:93], v[92:93], v[152:153], v[142:143] op_sel_hi:[1,1,0]
	v_add_u32_e32 v152, 48, v150
	v_ashrrev_i32_e32 v153, 31, v152
	v_pk_mul_f32 v[162:163], v[154:155], s[30:31] op_sel_hi:[1,0]
	v_lshl_add_u64 v[152:153], v[152:153], 2, s[4:5]
	v_cndmask_b32_e32 v155, v155, v163, vcc
	v_cndmask_b32_e64 v154, v154, v162, s[2:3]
	v_pk_fma_f32 v[86:87], v[86:87], v[154:155], v[146:147] op_sel_hi:[1,1,0]
	v_pk_fma_f32 v[82:83], v[82:83], v[154:155], v[144:145] op_sel_hi:[1,1,0]
	v_pk_fma_f32 v[94:95], v[94:95], v[154:155], v[142:143] op_sel_hi:[1,1,0]
	v_pk_fma_f32 v[90:91], v[90:91], v[154:155], v[132:133] op_sel_hi:[1,1,0]
	v_add_u32_e32 v154, 49, v150
	v_ashrrev_i32_e32 v155, 31, v154
	v_lshl_add_u64 v[154:155], v[154:155], 2, s[4:5]
	v_mov_b32_e32 v152, v232
	s_nop 0
	v_mov_b32_e32 v153, v233
	s_waitcnt vmcnt(0)
	v_pk_fma_f32 v[152:153], v[152:153], s[26:27], v[148:149] op_sel_hi:[1,0,0]
	s_nop 0
	v_mul_f32_e32 v143, 0x4b800000, v152
	v_cmp_gt_f32_e64 s[2:3], s6, v152
	v_cmp_gt_f32_e32 vcc, s6, v153
	s_nop 0
	v_cndmask_b32_e64 v143, v152, v143, s[2:3]
	v_rsq_f32_e32 v152, v143
	v_mul_f32_e32 v143, 0x4b800000, v153
	v_cndmask_b32_e32 v143, v153, v143, vcc
	v_rsq_f32_e32 v153, v143
	s_nop 0
	v_pk_mul_f32 v[154:155], v[152:153], s[30:31] op_sel_hi:[1,0]
	s_nop 0
	v_cndmask_b32_e64 v152, v152, v154, s[2:3]
	v_add_u32_e32 v154, 50, v150
	v_add_u32_e32 v150, 51, v150
	v_cndmask_b32_e32 v153, v153, v155, vcc
	v_ashrrev_i32_e32 v155, 31, v154
	v_ashrrev_i32_e32 v151, 31, v150
	v_lshl_add_u64 v[154:155], v[154:155], 2, s[4:5]
	v_lshl_add_u64 v[150:151], v[150:151], 2, s[4:5]
	v_mov_b32_e32 v154, v234
	v_pk_fma_f32 v[68:69], v[68:69], v[152:153], v[146:147] op_sel_hi:[1,1,0]
	v_mov_b32_e32 v155, v235
	v_pk_fma_f32 v[64:65], v[64:65], v[152:153], v[144:145] op_sel_hi:[1,1,0]
	v_pk_fma_f32 v[72:73], v[72:73], v[152:153], v[132:133] op_sel_hi:[1,1,0]
	s_waitcnt vmcnt(0)
	v_pk_fma_f32 v[148:149], v[154:155], s[26:27], v[148:149] op_sel_hi:[1,0,0]
	s_nop 0
	v_mul_f32_e32 v143, 0x4b800000, v148
	v_cmp_gt_f32_e64 s[2:3], s6, v148
	v_cmp_gt_f32_e32 vcc, s6, v149
	s_nop 0
	v_cndmask_b32_e64 v143, v148, v143, s[2:3]
	v_rsq_f32_e32 v148, v143
	v_mul_f32_e32 v143, 0x4b800000, v149
	v_cndmask_b32_e32 v143, v149, v143, vcc
	v_rsq_f32_e32 v149, v143
	v_pk_fma_f32 v[76:77], v[76:77], v[152:153], v[142:143] op_sel_hi:[1,1,0]
	v_pk_mul_f32 v[150:151], v[148:149], s[30:31] op_sel_hi:[1,0]
	s_nop 0
	v_cndmask_b32_e32 v149, v149, v151, vcc
	v_cndmask_b32_e64 v148, v148, v150, s[2:3]
	v_pk_fma_f32 v[70:71], v[70:71], v[148:149], v[146:147] op_sel_hi:[1,1,0]
	v_pk_fma_f32 v[66:67], v[66:67], v[148:149], v[144:145] op_sel_hi:[1,1,0]
	v_pk_fma_f32 v[78:79], v[78:79], v[148:149], v[142:143] op_sel_hi:[1,1,0]
	v_pk_fma_f32 v[74:75], v[74:75], v[148:149], v[132:133] op_sel_hi:[1,1,0]
	s_mov_b64 s[2:3], 0x1000
	s_branch .LBB0_1094

; __device__ __forceinline__ void norm_fix(f32x4 (&acc)[4][4], const float* rowss, const float* shW, int N, int brow, int bcol,
;                                          int wr, int wc, int fr, int fq) {
;   int mr = brow >> 12;
;   float sw[4];
; #pragma unroll
;   for (int n = 0; n < 4; n++) sw[n] = shW[(size_t)mr * N + bcol + (n >> 1) * 128 + wc * 32 + (n & 1) * 16 + fr];
; #pragma unroll
;   for (int m = 0; m < 4; m++)
; #pragma unroll
;     for (int j = 0; j < 4; j++) {
;       float rs = rsqrtf(rowss[brow + wr * 64 + m * 16 + fq * 4 + j] * (1.f / D) + 1e-6f);
; #pragma unroll
;       for (int n = 0; n < 4; n++) acc[m][n][j] = acc[m][n][j] * rs + sw[n];
;     }
.LBB0_1108:
	s_cmpk_gt_i32 s46, 0x7f7f
	s_cselect_b64 s[82:83], -1, 0
	s_cmpk_lt_i32 s46, 0x7f80
	s_cselect_b64 s[58:59], -1, 0
	s_and_b64 vcc, exec, s[82:83]
	s_cbranch_vccnz .LBB0_1110
	s_ashr_i32 s2, s36, 12
	s_ashr_i32 s3, s2, 31
	s_lshl_b64 s[2:3], s[2:3], 13
	s_add_u32 s37, s35, s2
	s_addc_u32 s84, s90, s3
	s_lshl_b64 s[2:3], s[48:49], 2
	s_add_u32 s2, s37, s2
	s_addc_u32 s3, s84, s3
	s_lshl_b32 s37, s76, 2
	v_add_u32_e32 v74, s36, v145
	s_add_u32 s2, s2, s37
	v_ashrrev_i32_e32 v75, 31, v74
	s_addc_u32 s3, s3, 0
	v_lshl_add_u64 v[72:73], v[74:75], 2, s[4:5]
	global_load_dword v70, v161, s[2:3]
	global_load_dword v68, v161, s[2:3] offset:64
	global_load_dword v66, v161, s[2:3] offset:512
	global_load_dword v64, v161, s[2:3] offset:576
	global_load_dwordx4 v[224:227], v[72:73], off offset:64
	global_load_dwordx4 v[228:231], v[72:73], off offset:128
	global_load_dwordx4 v[232:235], v[72:73], off offset:192
	global_load_dwordx4 v[76:79], v[72:73], off
	s_mov_b32 s2, 0x358637bd
	v_mov_b64_e32 v[72:73], s[2:3]
	s_mov_b32 s47, 12
	s_movk_i32 s48, 0xfff
	s_waitcnt vmcnt(0)
	v_pk_fma_f32 v[76:77], v[76:77], s[26:27], v[72:73] op_sel_hi:[1,0,0]
	s_nop 0
	v_mul_f32_e32 v65, 0x4b800000, v76
	v_cmp_gt_f32_e64 s[2:3], s6, v76
	v_cmp_gt_f32_e32 vcc, s6, v77
	v_pk_fma_f32 v[78:79], v[78:79], s[26:27], v[72:73] op_sel_hi:[1,0,0]
	v_cndmask_b32_e64 v65, v76, v65, s[2:3]
	v_rsq_f32_e32 v76, v65
	v_mul_f32_e32 v65, 0x4b800000, v77
	v_cndmask_b32_e32 v65, v77, v65, vcc
	v_rsq_f32_e32 v77, v65
	v_mul_f32_e32 v65, 0x4b800000, v78
	v_pk_mul_f32 v[80:81], v[76:77], s[30:31] op_sel_hi:[1,0]
	s_nop 0
	v_cndmask_b32_e64 v76, v76, v80, s[2:3]
	v_cmp_gt_f32_e64 s[2:3], s6, v78
	v_cndmask_b32_e32 v77, v77, v81, vcc
	v_cmp_gt_f32_e32 vcc, s6, v79
	v_cndmask_b32_e64 v65, v78, v65, s[2:3]
	v_rsq_f32_e32 v78, v65
	v_mul_f32_e32 v65, 0x4b800000, v79
	v_cndmask_b32_e32 v65, v79, v65, vcc
	v_rsq_f32_e32 v79, v65
	v_pk_fma_f32 v[52:53], v[52:53], v[76:77], v[70:71] op_sel_hi:[1,1,0]
	v_pk_fma_f32 v[48:49], v[48:49], v[76:77], v[68:69] op_sel_hi:[1,1,0]
	v_pk_fma_f32 v[60:61], v[60:61], v[76:77], v[66:67] op_sel_hi:[1,1,0]
	v_pk_mul_f32 v[80:81], v[78:79], s[30:31] op_sel_hi:[1,0]
	v_pk_fma_f32 v[56:57], v[56:57], v[76:77], v[64:65] op_sel_hi:[1,1,0]
	v_cndmask_b32_e32 v79, v79, v81, vcc
	v_cndmask_b32_e64 v78, v78, v80, s[2:3]
	v_pk_fma_f32 v[54:55], v[54:55], v[78:79], v[70:71] op_sel_hi:[1,1,0]
	v_pk_fma_f32 v[50:51], v[50:51], v[78:79], v[68:69] op_sel_hi:[1,1,0]
	v_pk_fma_f32 v[62:63], v[62:63], v[78:79], v[66:67] op_sel_hi:[1,1,0]
	v_pk_fma_f32 v[58:59], v[58:59], v[78:79], v[64:65] op_sel_hi:[1,1,0]
	v_add_u32_e32 v76, 16, v74
	v_add_u32_e32 v78, 17, v74
	v_ashrrev_i32_e32 v77, 31, v76
	v_ashrrev_i32_e32 v79, 31, v78
	v_lshl_add_u64 v[76:77], v[76:77], 2, s[4:5]
	v_lshl_add_u64 v[78:79], v[78:79], 2, s[4:5]
	v_mov_b32_e32 v76, v224
	v_add_u32_e32 v80, 19, v74
	v_mov_b32_e32 v77, v225
	v_ashrrev_i32_e32 v81, 31, v80
	v_lshl_add_u64 v[80:81], v[80:81], 2, s[4:5]
	s_waitcnt vmcnt(0)
	v_pk_fma_f32 v[76:77], v[76:77], s[26:27], v[72:73] op_sel_hi:[1,0,0]
	s_nop 0
	v_mul_f32_e32 v65, 0x4b800000, v76
	v_cmp_gt_f32_e64 s[2:3], s6, v76
	v_cmp_gt_f32_e32 vcc, s6, v77
	s_nop 0
	v_cndmask_b32_e64 v65, v76, v65, s[2:3]
	v_rsq_f32_e32 v76, v65
	v_mul_f32_e32 v65, 0x4b800000, v77
	v_cndmask_b32_e32 v65, v77, v65, vcc
	v_rsq_f32_e32 v77, v65
	s_nop 0
	v_pk_mul_f32 v[78:79], v[76:77], s[30:31] op_sel_hi:[1,0]
	s_nop 0
	v_cndmask_b32_e64 v76, v76, v78, s[2:3]
	v_add_u32_e32 v78, 18, v74
	v_cndmask_b32_e32 v77, v77, v79, vcc
	v_ashrrev_i32_e32 v79, 31, v78
	v_lshl_add_u64 v[78:79], v[78:79], 2, s[4:5]
	v_mov_b32_e32 v78, v226
	v_pk_fma_f32 v[36:37], v[36:37], v[76:77], v[70:71] op_sel_hi:[1,1,0]
	v_mov_b32_e32 v79, v227
	v_pk_fma_f32 v[32:33], v[32:33], v[76:77], v[68:69] op_sel_hi:[1,1,0]
	v_pk_fma_f32 v[44:45], v[44:45], v[76:77], v[66:67] op_sel_hi:[1,1,0]
	s_waitcnt vmcnt(0)
	v_pk_fma_f32 v[78:79], v[78:79], s[26:27], v[72:73] op_sel_hi:[1,0,0]
	s_nop 0
	v_mul_f32_e32 v65, 0x4b800000, v78
	v_cmp_gt_f32_e64 s[2:3], s6, v78
	v_cmp_gt_f32_e32 vcc, s6, v79
	s_nop 0
	v_cndmask_b32_e64 v65, v78, v65, s[2:3]
	v_rsq_f32_e32 v78, v65
	v_mul_f32_e32 v65, 0x4b800000, v79
	v_cndmask_b32_e32 v65, v79, v65, vcc
	v_rsq_f32_e32 v79, v65
	v_pk_fma_f32 v[40:41], v[40:41], v[76:77], v[64:65] op_sel_hi:[1,1,0]
	v_add_u32_e32 v76, 32, v74
	v_ashrrev_i32_e32 v77, 31, v76
	v_pk_mul_f32 v[80:81], v[78:79], s[30:31] op_sel_hi:[1,0]
	v_lshl_add_u64 v[76:77], v[76:77], 2, s[4:5]
	v_cndmask_b32_e32 v79, v79, v81, vcc
	v_cndmask_b32_e64 v78, v78, v80, s[2:3]
	v_pk_fma_f32 v[38:39], v[38:39], v[78:79], v[70:71] op_sel_hi:[1,1,0]
	v_pk_fma_f32 v[34:35], v[34:35], v[78:79], v[68:69] op_sel_hi:[1,1,0]
	v_pk_fma_f32 v[46:47], v[46:47], v[78:79], v[66:67] op_sel_hi:[1,1,0]
	v_pk_fma_f32 v[42:43], v[42:43], v[78:79], v[64:65] op_sel_hi:[1,1,0]
	v_add_u32_e32 v78, 33, v74
	v_ashrrev_i32_e32 v79, 31, v78
	v_lshl_add_u64 v[78:79], v[78:79], 2, s[4:5]
	v_mov_b32_e32 v76, v228
	v_add_u32_e32 v80, 35, v74
	v_mov_b32_e32 v77, v229
	v_ashrrev_i32_e32 v81, 31, v80
	v_lshl_add_u64 v[80:81], v[80:81], 2, s[4:5]
	s_waitcnt vmcnt(0)
; __device__ __forceinline__ void norm_fix(f32x4 (&acc)[4][4], const float* rowss, const float* shW, int N, int brow, int bcol,
;                                          int wr, int wc, int fr, int fq) {
;   int mr = brow >> 12;
;   float sw[4];
; #pragma unroll
;   for (int n = 0; n < 4; n++) sw[n] = shW[(size_t)mr * N + bcol + (n >> 1) * 128 + wc * 32 + (n & 1) * 16 + fr];
; #pragma unroll
;   for (int m = 0; m < 4; m++)
; #pragma unroll
;     for (int j = 0; j < 4; j++) {
;       float rs = rsqrtf(rowss[brow + wr * 64 + m * 16 + fq * 4 + j] * (1.f / D) + 1e-6f);
; #pragma unroll
;       for (int n = 0; n < 4; n++) acc[m][n][j] = acc[m][n][j] * rs + sw[n];
;     }
	v_pk_fma_f32 v[76:77], v[76:77], s[26:27], v[72:73] op_sel_hi:[1,0,0]
	s_nop 0
	v_mul_f32_e32 v65, 0x4b800000, v76
	v_cmp_gt_f32_e64 s[2:3], s6, v76
	v_cmp_gt_f32_e32 vcc, s6, v77
	s_nop 0
	v_cndmask_b32_e64 v65, v76, v65, s[2:3]
	v_rsq_f32_e32 v76, v65
	v_mul_f32_e32 v65, 0x4b800000, v77
	v_cndmask_b32_e32 v65, v77, v65, vcc
	v_rsq_f32_e32 v77, v65
	s_nop 0
	v_pk_mul_f32 v[78:79], v[76:77], s[30:31] op_sel_hi:[1,0]
	s_nop 0
	v_cndmask_b32_e64 v76, v76, v78, s[2:3]
	v_add_u32_e32 v78, 34, v74
	v_cndmask_b32_e32 v77, v77, v79, vcc
	v_ashrrev_i32_e32 v79, 31, v78
	v_lshl_add_u64 v[78:79], v[78:79], 2, s[4:5]
	v_mov_b32_e32 v78, v230
	v_pk_fma_f32 v[20:21], v[20:21], v[76:77], v[70:71] op_sel_hi:[1,1,0]
	v_mov_b32_e32 v79, v231
	v_pk_fma_f32 v[16:17], v[16:17], v[76:77], v[68:69] op_sel_hi:[1,1,0]
	v_pk_fma_f32 v[28:29], v[28:29], v[76:77], v[66:67] op_sel_hi:[1,1,0]
	s_waitcnt vmcnt(0)
	v_pk_fma_f32 v[78:79], v[78:79], s[26:27], v[72:73] op_sel_hi:[1,0,0]
	s_nop 0
	v_mul_f32_e32 v65, 0x4b800000, v78
	v_cmp_gt_f32_e64 s[2:3], s6, v78
	v_cmp_gt_f32_e32 vcc, s6, v79
	s_nop 0
	v_cndmask_b32_e64 v65, v78, v65, s[2:3]
	v_rsq_f32_e32 v78, v65
	v_mul_f32_e32 v65, 0x4b800000, v79
	v_cndmask_b32_e32 v65, v79, v65, vcc
	v_rsq_f32_e32 v79, v65
	v_pk_fma_f32 v[24:25], v[24:25], v[76:77], v[64:65] op_sel_hi:[1,1,0]
	v_add_u32_e32 v76, 48, v74
	v_ashrrev_i32_e32 v77, 31, v76
	v_pk_mul_f32 v[80:81], v[78:79], s[30:31] op_sel_hi:[1,0]
	v_lshl_add_u64 v[76:77], v[76:77], 2, s[4:5]
	v_cndmask_b32_e32 v79, v79, v81, vcc
	v_cndmask_b32_e64 v78, v78, v80, s[2:3]
	v_pk_fma_f32 v[22:23], v[22:23], v[78:79], v[70:71] op_sel_hi:[1,1,0]
	v_pk_fma_f32 v[18:19], v[18:19], v[78:79], v[68:69] op_sel_hi:[1,1,0]
	v_pk_fma_f32 v[30:31], v[30:31], v[78:79], v[66:67] op_sel_hi:[1,1,0]
	v_pk_fma_f32 v[26:27], v[26:27], v[78:79], v[64:65] op_sel_hi:[1,1,0]
	v_add_u32_e32 v78, 49, v74
	v_ashrrev_i32_e32 v79, 31, v78
	v_lshl_add_u64 v[78:79], v[78:79], 2, s[4:5]
	v_mov_b32_e32 v76, v232
	s_nop 0
	v_mov_b32_e32 v77, v233
	s_waitcnt vmcnt(0)
	v_pk_fma_f32 v[76:77], v[76:77], s[26:27], v[72:73] op_sel_hi:[1,0,0]
	s_nop 0
	v_mul_f32_e32 v65, 0x4b800000, v76
	v_cmp_gt_f32_e64 s[2:3], s6, v76
	v_cmp_gt_f32_e32 vcc, s6, v77
	s_nop 0
	v_cndmask_b32_e64 v65, v76, v65, s[2:3]
	v_rsq_f32_e32 v76, v65
	v_mul_f32_e32 v65, 0x4b800000, v77
	v_cndmask_b32_e32 v65, v77, v65, vcc
	v_rsq_f32_e32 v77, v65
	s_nop 0
	v_pk_mul_f32 v[78:79], v[76:77], s[30:31] op_sel_hi:[1,0]
	s_nop 0
	v_cndmask_b32_e64 v76, v76, v78, s[2:3]
	v_add_u32_e32 v78, 50, v74
	v_add_u32_e32 v74, 51, v74
	v_cndmask_b32_e32 v77, v77, v79, vcc
	v_ashrrev_i32_e32 v79, 31, v78
	v_ashrrev_i32_e32 v75, 31, v74
	v_lshl_add_u64 v[78:79], v[78:79], 2, s[4:5]
	v_lshl_add_u64 v[74:75], v[74:75], 2, s[4:5]
	v_mov_b32_e32 v78, v234
	v_pk_fma_f32 v[4:5], v[4:5], v[76:77], v[70:71] op_sel_hi:[1,1,0]
	v_mov_b32_e32 v79, v235
	v_pk_fma_f32 v[0:1], v[0:1], v[76:77], v[68:69] op_sel_hi:[1,1,0]
	v_pk_fma_f32 v[12:13], v[12:13], v[76:77], v[66:67] op_sel_hi:[1,1,0]
	s_waitcnt vmcnt(0)
	v_pk_fma_f32 v[72:73], v[78:79], s[26:27], v[72:73] op_sel_hi:[1,0,0]
	s_nop 0
	v_mul_f32_e32 v65, 0x4b800000, v72
	v_cmp_gt_f32_e64 s[2:3], s6, v72
	v_cmp_gt_f32_e32 vcc, s6, v73
	s_nop 0
	v_cndmask_b32_e64 v65, v72, v65, s[2:3]
	v_rsq_f32_e32 v72, v65
	v_mul_f32_e32 v65, 0x4b800000, v73
	v_cndmask_b32_e32 v65, v73, v65, vcc
	v_rsq_f32_e32 v73, v65
	v_pk_fma_f32 v[8:9], v[8:9], v[76:77], v[64:65] op_sel_hi:[1,1,0]
	v_pk_mul_f32 v[74:75], v[72:73], s[30:31] op_sel_hi:[1,0]
	s_nop 0
	v_cndmask_b32_e32 v73, v73, v75, vcc
	v_cndmask_b32_e64 v72, v72, v74, s[2:3]
	v_pk_fma_f32 v[6:7], v[6:7], v[72:73], v[70:71] op_sel_hi:[1,1,0]
	v_pk_fma_f32 v[2:3], v[2:3], v[72:73], v[68:69] op_sel_hi:[1,1,0]
	v_pk_fma_f32 v[14:15], v[14:15], v[72:73], v[66:67] op_sel_hi:[1,1,0]
	v_pk_fma_f32 v[10:11], v[10:11], v[72:73], v[64:65] op_sel_hi:[1,1,0]
	s_mov_b64 s[2:3], 0x1000
	s_branch .LBB0_1111
